# speedup vs baseline: 1.0008x; 1.0008x over previous
; __global__ void __launch_bounds__(NTHREADS) fwd_megakernel(Params p) {
;     ...
;   int pend_d = 0;
;   if (tid == 0) pend_d = (int)atomicAdd(&ctr[16], 1u);
;   for (;;) {
;     __syncthreads();
;     if (tid == 0) s_item = pend_d;
;     __syncthreads();
;     const int it = s_item;
;     if (it >= T_TOK / 8) break;
;     if (tid == 0) pend_d = (int)atomicAdd(&ctr[16], 1u);
;     const int b = it & 1, grp = 511 - (it >> 1);
;     ...
;     dsa_item(p, b * SEQ + grp * 8);
;     ...
;   }
.LBB0_2221:
	v_readfirstlane_b32 s98, v194
	s_nop 3
	s_lshr_b32 s98, s98, 6
	s_cmp_ge_u32 s98, 4
	s_cbranch_scc0 .Ldsa_prio_done
	s_setprio 1

; __device__ __forceinline__ unsigned xb_add(unsigned* p, unsigned v) { return __hip_atomic_fetch_add(p, v, __ATOMIC_RELAXED, __HIP_MEMORY_SCOPE_AGENT); }
; __device__ __forceinline__ void xcd_barrier(const XcdBarrier& b) {
;   asm volatile("s_waitcnt vmcnt(0)" ::: "memory");
;   __syncthreads();
;   if (threadIdx.x == 0) {
;     unsigned* bar = b.bar;
;     __builtin_amdgcn_s_waitcnt(0);
;     const unsigned old = xb_add(&bar[XB_XSUB(b.x)], 1u);
; __global__ void __launch_bounds__(NTHREADS) fwd_megakernel(Params p) {
;     ...
;   xcd_barrier(xb);
.LBB0_3048:
	s_setprio 0
	s_waitcnt vmcnt(0)
	s_barrier
	s_and_saveexec_b64 s[2:3], s[0:1]
	s_cbranch_execz .LBB0_3085
	s_mov_b64 s[4:5], exec
	v_mbcnt_lo_u32_b32 v0, s4, 0
	v_readlane_b32 s6, v241, 35
	v_mbcnt_hi_u32_b32 v0, s5, v0
	s_lshl_b32 s22, s6, 6
	s_mov_b32 s9, 0
	v_cmp_eq_u32_e32 vcc, 0, v0
	s_waitcnt vmcnt(0) expcnt(0) lgkmcnt(0)
	s_and_saveexec_b64 s[6:7], vcc
	s_cbranch_execz .LBB0_3051
	s_add_i32 s8, s22, 0x500
	s_lshl_b64 s[8:9], s[8:9], 2
	v_readlane_b32 s10, v241, 33
	v_readlane_b32 s11, v241, 34
	s_add_u32 s8, s10, s8
	s_addc_u32 s9, s11, s9
	s_bcnt1_i32_b64 s4, s[4:5]
	v_mov_b32_e32 v1, 0
	v_mov_b32_e32 v2, s4
	global_atomic_add v1, v1, v2, s[8:9] sc0
